# speedup vs baseline: 1.0072x; 1.0011x over previous
; __device__ __forceinline__ int tid_() { int t = threadIdx.x; asm volatile("" : "+v"(t)); return t; }
; __device__ __forceinline__ void phase_final(float* x, const float* g, int bid, int nb) {
;   const int tidn = tid_();
;   int wid = tidn >> 6, lane = tidn & 63;
;   for (int r = bid * 8 + wid; r < T_ALL; r += nb * 8) {
;     float* xr = x + (long)r * D;
;     float4 v[4];
;     float ss = 0.f;
; #pragma unroll
;     for (int i = 0; i < 4; ++i) {
;       v[i] = *(const float4*)(xr + i * 256 + lane * 4);
;       ss += v[i].x * v[i].x + v[i].y * v[i].y + v[i].z * v[i].z + v[i].w * v[i].w;
;     }
; #pragma unroll
;     for (int o = 32; o >= 1; o >>= 1) ss += shfl_xor_l(ss, lane, o);
;     float rinv = rsqrtf(ss * (1.0f / D) + EPS);
; #pragma unroll
;     for (int i = 0; i < 4; ++i) {
;       float4 gg = *(const float4*)(g + i * 256 + lane * 4);
;       float4 o = make_float4(v[i].x * rinv * gg.x, v[i].y * rinv * gg.y, v[i].z * rinv * gg.z, v[i].w * rinv * gg.w);
;       *(float4*)(xr + i * 256 + lane * 4) = o;
;     }
;   }
; }
.LBB0_10:
	s_cmpk_eq_i32 s42, 0x43
	s_mov_b64 s[6:7], -1
	s_cbranch_scc0 .LBB0_15
	v_mov_b32_e32 v12, v182
	s_mov_b32 s6, 0x14000
	s_waitcnt vmcnt(0) lgkmcnt(0)
	v_ashrrev_i32_e32 v4, 6, v12
	v_add_u32_e32 v6, s60, v4
	v_cmp_gt_i32_e32 vcc, s6, v6
	s_and_saveexec_b64 s[6:7], vcc
	v_readlane_b32 s16, v249, 9
	v_readlane_b32 s17, v249, 10
	s_mov_b32 s18, 0x800000
	s_cbranch_execz .LBB0_14
	v_lshlrev_b32_e32 v5, 2, v12
	v_and_b32_e32 v0, 0xfc, v5
	v_readlane_b32 s8, v250, 4
	v_lshlrev_b32_e32 v0, 2, v0
	v_readlane_b32 s14, v250, 10
	v_readlane_b32 s15, v250, 11
	s_movk_i32 s8, 0x80
	v_bitop3_b32 v7, v5, 64, v185 bitop3:0x6c
	v_lshl_add_u64 v[2:3], s[14:15], 0, v[0:1]
	v_bitop3_b32 v0, v5, s8, v185 bitop3:0x6c
	v_bitop3_b32 v8, v5, 32, v185 bitop3:0x6c
	v_bitop3_b32 v9, v5, 16, v185 bitop3:0x6c
	v_bitop3_b32 v10, v5, 8, v185 bitop3:0x6c
	v_bitop3_b32 v11, v5, 4, v185 bitop3:0x6c
	v_ashrrev_i32_e32 v5, 31, v4
	v_readlane_b32 s9, v250, 5
	v_readlane_b32 s10, v250, 6
	v_readlane_b32 s11, v250, 7
	v_lshl_add_u64 v[4:5], s[60:61], 0, v[4:5]
	v_lshlrev_b64 v[4:5], 12, v[4:5]
	v_and_b32_e32 v12, 63, v12
	v_readlane_b32 s8, v250, 0
	v_lshl_or_b32 v4, v12, 4, v4
	v_readlane_b32 s9, v250, 1
	v_readlane_b32 s12, v250, 8
	v_readlane_b32 s13, v250, 9
	v_lshl_add_u64 v[4:5], s[8:9], 0, v[4:5]
	s_mov_b64 s[8:9], 0
	v_readlane_b32 s10, v250, 2
	v_readlane_b32 s11, v250, 3
	global_load_dwordx4 v[216:219], v[2:3], off
	global_load_dwordx4 v[196:199], v[2:3], off offset:1024
	global_load_dwordx4 v[200:203], v[2:3], off offset:2048
	global_load_dwordx4 v[204:207], v[2:3], off offset:3072
.LBB0_13:
	global_load_dwordx4 v[12:15], v[4:5], off
	global_load_dwordx4 v[20:23], v[4:5], off offset:1024
	global_load_dwordx4 v[208:211], v[4:5], off offset:2048
	global_load_dwordx4 v[212:215], v[4:5], off offset:3072
	v_add_u32_e32 v6, s62, v6
	s_mov_b32 s10, 0x13fff
	s_waitcnt vmcnt(0)
	v_mov_b64_e32 v[16:17], v[216:217]
	v_mov_b64_e32 v[18:19], v[218:219]
	v_mov_b32_e32 v26, v13
	v_mov_b32_e32 v24, v12
	s_waitcnt vmcnt(0)
	v_mov_b32_e32 v27, v21
	v_mov_b32_e32 v25, v20
	v_pk_mul_f32 v[26:27], v[26:27], v[26:27]
	v_mov_b32_e32 v28, v15
	v_pk_fma_f32 v[24:25], v[24:25], v[24:25], v[26:27]
	v_mov_b32_e32 v26, v14
	v_mov_b32_e32 v27, v22
	v_mov_b32_e32 v29, v23
	v_pk_fma_f32 v[24:25], v[26:27], v[26:27], v[24:25]
	s_nop 0
	v_pk_fma_f32 v[32:33], v[28:29], v[28:29], v[24:25]
	v_mov_b64_e32 v[24:25], v[208:209]
	v_mov_b64_e32 v[26:27], v[210:211]
	v_mov_b64_e32 v[28:29], v[212:213]
	v_mov_b64_e32 v[30:31], v[214:215]
	v_add_f32_e32 v32, v32, v33
	s_waitcnt vmcnt(1)
	v_mov_b32_e32 v36, v25
	s_waitcnt vmcnt(0)
	v_mov_b32_e32 v37, v29
	v_mov_b32_e32 v34, v24
	v_mov_b32_e32 v35, v28
	v_pk_mul_f32 v[36:37], v[36:37], v[36:37]
	v_mov_b32_e32 v38, v27
	v_pk_fma_f32 v[34:35], v[34:35], v[34:35], v[36:37]
	v_mov_b32_e32 v36, v26
	v_mov_b32_e32 v37, v30
	v_mov_b32_e32 v39, v31
	v_pk_fma_f32 v[34:35], v[36:37], v[36:37], v[34:35]
	s_nop 0
	v_pk_fma_f32 v[34:35], v[38:39], v[38:39], v[34:35]
	s_nop 0
	v_add_f32_e32 v32, v32, v34
	v_add_f32_e32 v32, v32, v35
	ds_bpermute_b32 v33, v0, v32
	s_waitcnt lgkmcnt(0)
	v_add_f32_e32 v32, v32, v33
	ds_bpermute_b32 v33, v7, v32
	s_waitcnt lgkmcnt(0)
	v_add_f32_e32 v32, v32, v33
	ds_bpermute_b32 v33, v8, v32
	s_waitcnt lgkmcnt(0)
	v_add_f32_e32 v32, v32, v33
	ds_bpermute_b32 v33, v9, v32
	s_waitcnt lgkmcnt(0)
	v_add_f32_e32 v32, v32, v33
	ds_bpermute_b32 v33, v10, v32
	s_waitcnt lgkmcnt(0)
	v_add_f32_e32 v32, v32, v33
	ds_bpermute_b32 v33, v11, v32
	s_waitcnt lgkmcnt(0)
	v_add_f32_e32 v32, v32, v33
	v_fmamk_f32 v32, v32, 0x3a800000, v183
	v_cmp_gt_f32_e32 vcc, s18, v32
	v_mul_f32_e32 v33, 0x4b800000, v32
	s_nop 0
	v_cndmask_b32_e32 v32, v32, v33, vcc
	v_rsq_f32_e32 v32, v32
	s_nop 0
	v_mul_f32_e32 v33, 0x45800000, v32
	v_cndmask_b32_e32 v32, v32, v33, vcc
	v_pk_mul_f32 v[12:13], v[12:13], v[32:33] op_sel_hi:[1,0]
	v_pk_mul_f32 v[14:15], v[14:15], v[32:33] op_sel_hi:[1,0]
	v_pk_mul_f32 v[12:13], v[16:17], v[12:13]
	v_pk_mul_f32 v[14:15], v[18:19], v[14:15]
	global_store_dwordx4 v[4:5], v[12:15], off
	s_nop 1
	v_mov_b64_e32 v[12:13], v[196:197]
	v_mov_b64_e32 v[14:15], v[198:199]
	v_pk_mul_f32 v[16:17], v[20:21], v[32:33] op_sel_hi:[1,0]
	v_cmp_lt_i32_e32 vcc, s10, v6
	s_or_b64 s[8:9], vcc, s[8:9]
	s_nop 0
	v_pk_mul_f32 v[12:13], v[12:13], v[16:17]
	v_pk_mul_f32 v[16:17], v[22:23], v[32:33] op_sel_hi:[1,0]
	s_nop 0
	v_pk_mul_f32 v[14:15], v[14:15], v[16:17]
	global_store_dwordx4 v[4:5], v[12:15], off offset:1024
	s_nop 1
	v_mov_b64_e32 v[12:13], v[200:201]
	v_mov_b64_e32 v[14:15], v[202:203]
	v_pk_mul_f32 v[16:17], v[24:25], v[32:33] op_sel_hi:[1,0]
	s_nop 0
	v_pk_mul_f32 v[12:13], v[16:17], v[12:13]
	v_pk_mul_f32 v[16:17], v[26:27], v[32:33] op_sel_hi:[1,0]
	s_nop 0
	v_pk_mul_f32 v[14:15], v[16:17], v[14:15]
	global_store_dwordx4 v[4:5], v[12:15], off offset:2048
	s_nop 1
	v_mov_b64_e32 v[12:13], v[204:205]
	v_mov_b64_e32 v[14:15], v[206:207]
	v_pk_mul_f32 v[16:17], v[28:29], v[32:33] op_sel_hi:[1,0]
	s_nop 0
	v_pk_mul_f32 v[12:13], v[16:17], v[12:13]
	v_pk_mul_f32 v[16:17], v[30:31], v[32:33] op_sel_hi:[1,0]
	s_nop 0
	v_pk_mul_f32 v[14:15], v[16:17], v[14:15]
	global_store_dwordx4 v[4:5], v[12:15], off offset:3072
	v_lshl_add_u64 v[4:5], v[4:5], 0, s[16:17]
	s_andn2_b64 exec, exec, s[8:9]
	s_cbranch_execnz .LBB0_13

; __device__ __forceinline__ void run_phase(const Params& P, char* shm, int ph, int bid, int nb) {
;   if (ph == 0) { phase_prep(P, shm, bid, nb); return; }
;   if (ph == N_PHASES - 1) { phase_final(P.x, P.final_g, bid, nb); return; }
;   int q = ph - 1;
;   int grp = q / PH_PER_GRP;
;   int qq = q % PH_PER_GRP;
;   float* xg = P.x + (long)P.gtok0 * D;
;   const int nM = P.tg / 256;
;   if (qq == 0) { phase_x0(P, P.gtok0, xg, P.xn, P.sq1, P.tg, bid, nb); return; }
;   int l = (qq - 1) / PH_PER_LAYER;
;   int s = (qq - 1) % PH_PER_LAYER;
;   switch (s) {
; template <bool COOP>
; __global__ void __launch_bounds__(NTHR) mega(KArgs K, int ph_lo, int ph_hi) {
;     ...
;       const int grp = (ph - 1) / PH_PER_GRP;
;       P.tg = grp <= 0 ? TG0 : TG1;
;       P.gtok0 = grp <= 0 ? 0 : TG0;
.LBB0_17:
	s_cmp_lt_i32 s42, 34
	s_mov_b32 s4, 0xc000
	s_cselect_b32 s93, s4, 0x8000
	s_cselect_b32 s75, 0, 0xc000
	s_add_i32 s4, s42, -1
	s_mul_hi_i32 s5, s4, 0x3e0f83e1
	s_lshr_b32 s6, s5, 31
	s_ashr_i32 s5, s5, 3
	s_add_i32 s5, s5, s6
	s_mul_i32 s5, s5, 33
	s_sub_i32 s27, s4, s5
	s_lshl_b32 s4, s75, 12
	s_mov_b32 s5, s59
	s_cmp_lg_u32 s27, 0
	v_writelane_b32 v249, s4, 56
	s_nop 1
	v_writelane_b32 v249, s5, 57
	s_cbranch_scc0 .LBB0_53
	s_add_i32 s4, s27, -1
	s_bfe_i32 s5, s4, 0x80000
	s_bfe_u32 s5, s5, 0x3000c
	s_add_i32 s5, s4, s5
	s_bfe_i32 s6, s5, 0x80000
	s_sext_i32_i16 s6, s6
	s_and_b32 s5, s5, 0xf8
	s_lshr_b32 s45, s6, 3
	s_ashr_i32 s6, s6, 3
	s_sub_i32 s4, s4, s5
	v_writelane_b32 v249, s6, 58
	s_and_b32 s28, s4, 0xff
	s_lshr_b32 s4, s93, 8
	v_writelane_b32 v249, s4, 59
	s_add_u32 s4, s2, 0x8400800
	s_addc_u32 s5, s3, 0
	s_add_u32 s54, s2, 0x30e00000
	s_addc_u32 s55, s3, 0
	s_add_u32 s12, s2, 0x3ce00000
	v_writelane_b32 v249, s4, 60
	s_addc_u32 s13, s3, 0
	v_writelane_b32 v248, s54, 0
	v_writelane_b32 v249, s5, 61
	s_add_u32 s4, s2, 0x4dc04040
	v_writelane_b32 v249, s4, 62
	s_addc_u32 s4, s3, 0
	v_writelane_b32 v249, s4, 63
	s_cmp_lt_i32 s28, 4
	s_mov_b64 s[4:5], -1
	v_writelane_b32 v248, s55, 1
	s_cbranch_scc1 .LBB0_150
	v_readlane_b32 s4, v250, 0
	v_readlane_b32 s6, v250, 2
	v_readlane_b32 s7, v250, 3
	v_readlane_b32 s6, v249, 56
	v_readlane_b32 s5, v250, 1
	v_readlane_b32 s7, v249, 57
	s_add_u32 s6, s4, s6
	s_addc_u32 s7, s5, 0
	s_add_u32 s29, s2, 0x4df14040
	s_addc_u32 s30, s3, 0
	s_and_b32 s31, 0xffff, s28
	s_cmp_lt_i32 s31, 6
	s_mov_b64 s[4:5], -1
	s_cbranch_scc1 .LBB0_85
	s_cmp_lt_i32 s31, 7
	s_cbranch_scc1 .LBB0_55
	s_cmp_eq_u32 s31, 7
	s_cbranch_scc0 .LBB0_54
	s_lshr_b32 s16, s93, 6
	v_readlane_b32 s4, v249, 1
	s_cmp_ge_i32 s4, s16
	s_cbranch_scc1 .LBB0_54
	v_readlane_b32 s4, v249, 58
	s_mul_i32 s4, s4, 0x2c0000
	s_ashr_i32 s5, s4, 31
	s_lshl_b64 s[4:5], s[4:5], 1
	v_readlane_b32 s8, v249, 52
	v_readlane_b32 s9, v249, 53
	s_add_u32 s17, s8, s4
	s_addc_u32 s18, s9, s5
	s_add_u32 s19, s2, s4
	s_addc_u32 s20, s3, s5
	s_mov_b64 s[8:9], 0
	v_readlane_b32 s21, v249, 1
	s_branch .LBB0_25
	s_nop 0
	s_nop 0
	s_nop 0
	s_nop 0
	s_nop 0
	s_nop 0
	s_nop 0
	s_nop 0
	s_nop 0
	s_nop 0
	s_nop 0
	s_nop 0
	s_nop 0
	s_nop 0
	s_nop 0
	s_nop 0
	s_nop 0
	s_nop 0
	s_nop 0
	s_nop 0
	s_nop 0
	s_nop 0
	s_nop 0
	s_nop 0
	s_nop 0
	s_nop 0
	s_nop 0
	s_nop 0
	s_nop 0
	s_nop 0
	s_nop 0
	s_nop 0
	s_nop 0
	s_nop 0
	s_nop 0
	s_nop 0
	s_nop 0
	s_nop 0
	s_nop 0
	s_nop 0
	s_nop 0
	s_nop 0
	s_nop 0
	s_nop 0
	s_nop 0
	s_nop 0
	s_nop 0
	s_nop 0
	s_nop 0
	s_nop 0
	s_nop 0
	s_nop 0
	s_nop 0
	s_nop 0
	s_nop 0
	s_nop 0
	s_nop 0
	s_nop 0
	s_nop 0
	s_nop 0
	s_nop 0
	s_nop 0
	s_nop 0
	s_nop 0
	s_nop 0
	s_nop 0
	s_nop 0
	s_nop 0
	s_nop 0
	s_nop 0
	s_nop 0
	s_nop 0
	s_nop 0
	s_nop 0
	s_nop 0
	s_nop 0
	s_nop 0
	s_nop 0
	s_nop 0
	s_nop 0
	s_nop 0
	s_nop 0
	s_nop 0
	s_nop 0
	s_nop 0
	s_nop 0
	s_nop 0
	s_nop 0
	s_nop 0
	s_nop 0
	s_nop 0
	s_nop 0
	s_nop 0
	s_nop 0
	s_nop 0
	s_nop 0
	s_nop 0
	s_nop 0
	s_nop 0
	s_nop 0
	s_nop 0
	s_nop 0
	s_nop 0
	s_nop 0
	s_nop 0
	s_nop 0
	s_nop 0
	s_nop 0
	s_nop 0
	s_nop 0
	s_nop 0
	s_nop 0
	s_nop 0
